# S4 GLU epilogue: single vmcnt(0) per load group instead of per-block waits on earlier stores; KV K-path row-scale loads prefetched together
# baseline (speedup 1.0000x reference)
.LBB7_334:
	s_nop 0
	v_lshl_add_u64 v[128:129], v[168:169], 2, s[8:9]
	global_load_dword v224, v[128:129], off
	global_load_dword v225, v[128:129], off offset:64
	global_load_dword v226, v[128:129], off offset:128
	global_load_dword v227, v[128:129], off offset:192
	global_load_dword v228, v[128:129], off offset:512
	global_load_dword v229, v[128:129], off offset:576
	global_load_dword v230, v[128:129], off offset:640
	global_load_dword v231, v[128:129], off offset:704
	v_readlane_b32 s40, v251, 10
	s_add_u32 s38, s40, s38
	v_readlane_b32 s40, v251, 11
	s_addc_u32 s39, s40, s39
	v_lshlrev_b64 v[130:131], 11, v[168:169]
	v_lshl_add_u64 v[136:137], v[166:167], 1, s[38:39]
	v_lshl_add_u64 v[130:131], v[136:137], 0, v[130:131]
	v_lshl_add_u64 v[134:135], v[164:165], 2, s[8:9]
	s_mov_b64 s[38:39], 0x40000
	s_waitcnt vmcnt(0)
	v_mov_b32_e32 v132, v224
	v_pk_mul_f32 v[126:127], v[126:127], v[132:133] op_sel_hi:[1,0]
	v_pk_mul_f32 v[124:125], v[124:125], v[132:133] op_sel_hi:[1,0]
	v_pk_mul_f32 v[122:123], v[122:123], v[132:133] op_sel_hi:[1,0]
	v_pk_mul_f32 v[120:121], v[120:121], v[132:133] op_sel_hi:[1,0]
	v_pk_mul_f32 v[118:119], v[118:119], v[132:133] op_sel_hi:[1,0]
	v_pk_mul_f32 v[116:117], v[116:117], v[132:133] op_sel_hi:[1,0]
	v_pk_mul_f32 v[138:139], v[114:115], v[132:133] op_sel_hi:[1,0]
	v_pk_mul_f32 v[132:133], v[112:113], v[132:133] op_sel_hi:[1,0]
	v_cvt_pk_bf16_f32 v112, v124, v125
	v_cvt_pk_bf16_f32 v113, v126, v127
	v_cvt_pk_bf16_f32 v114, v120, v121
	v_cvt_pk_bf16_f32 v115, v122, v123
	global_store_dwordx4 v[130:131], v[112:115], off
	s_nop 1
	v_cvt_pk_bf16_f32 v112, v116, v117
	v_cvt_pk_bf16_f32 v113, v118, v119
	v_cvt_pk_bf16_f32 v114, v132, v133
	v_cvt_pk_bf16_f32 v115, v138, v139
	global_store_dwordx4 v[130:131], v[112:115], off offset:256
	s_nop 0
	v_lshl_add_u64 v[116:117], v[162:163], 2, s[8:9]
	v_lshlrev_b64 v[114:115], 11, v[164:165]
	v_lshl_add_u64 v[114:115], v[136:137], 0, v[114:115]
	s_nop 0
	v_mov_b32_e32 v112, v225
	v_pk_mul_f32 v[110:111], v[110:111], v[112:113] op_sel_hi:[1,0]
	v_pk_mul_f32 v[108:109], v[108:109], v[112:113] op_sel_hi:[1,0]
	v_pk_mul_f32 v[106:107], v[106:107], v[112:113] op_sel_hi:[1,0]
	v_pk_mul_f32 v[104:105], v[104:105], v[112:113] op_sel_hi:[1,0]
	v_pk_mul_f32 v[102:103], v[102:103], v[112:113] op_sel_hi:[1,0]
	v_pk_mul_f32 v[100:101], v[100:101], v[112:113] op_sel_hi:[1,0]
	v_pk_mul_f32 v[118:119], v[98:99], v[112:113] op_sel_hi:[1,0]
	v_pk_mul_f32 v[112:113], v[96:97], v[112:113] op_sel_hi:[1,0]
	v_cvt_pk_bf16_f32 v96, v108, v109
	v_cvt_pk_bf16_f32 v97, v110, v111
	v_cvt_pk_bf16_f32 v98, v104, v105
	v_cvt_pk_bf16_f32 v99, v106, v107
	global_store_dwordx4 v[114:115], v[96:99], off
	s_nop 1
	v_cvt_pk_bf16_f32 v96, v100, v101
	v_cvt_pk_bf16_f32 v97, v102, v103
	v_cvt_pk_bf16_f32 v98, v112, v113
	v_cvt_pk_bf16_f32 v99, v118, v119
	global_store_dwordx4 v[114:115], v[96:99], off offset:256
	s_nop 0
	v_lshl_add_u64 v[100:101], v[160:161], 2, s[8:9]
	v_lshlrev_b64 v[98:99], 11, v[162:163]
	v_lshl_add_u64 v[98:99], v[136:137], 0, v[98:99]
	s_nop 0
	v_mov_b32_e32 v96, v226
	v_pk_mul_f32 v[94:95], v[94:95], v[96:97] op_sel_hi:[1,0]
	v_pk_mul_f32 v[92:93], v[92:93], v[96:97] op_sel_hi:[1,0]
	v_pk_mul_f32 v[90:91], v[90:91], v[96:97] op_sel_hi:[1,0]
	v_pk_mul_f32 v[88:89], v[88:89], v[96:97] op_sel_hi:[1,0]
	v_pk_mul_f32 v[86:87], v[86:87], v[96:97] op_sel_hi:[1,0]
	v_pk_mul_f32 v[84:85], v[84:85], v[96:97] op_sel_hi:[1,0]
	v_pk_mul_f32 v[102:103], v[82:83], v[96:97] op_sel_hi:[1,0]
	v_pk_mul_f32 v[96:97], v[80:81], v[96:97] op_sel_hi:[1,0]
	v_cvt_pk_bf16_f32 v80, v92, v93
	v_cvt_pk_bf16_f32 v81, v94, v95
	v_cvt_pk_bf16_f32 v82, v88, v89
	v_cvt_pk_bf16_f32 v83, v90, v91
	global_store_dwordx4 v[98:99], v[80:83], off
	s_nop 1
	v_cvt_pk_bf16_f32 v80, v84, v85
	v_cvt_pk_bf16_f32 v81, v86, v87
	v_cvt_pk_bf16_f32 v82, v96, v97
	v_cvt_pk_bf16_f32 v83, v102, v103
	global_store_dwordx4 v[98:99], v[80:83], off offset:256
	s_nop 0
	s_nop 0
	v_mov_b32_e32 v80, v227
	v_pk_mul_f32 v[78:79], v[78:79], v[80:81] op_sel_hi:[1,0]
	v_lshlrev_b64 v[82:83], 11, v[160:161]
	v_lshl_add_u64 v[82:83], v[136:137], 0, v[82:83]
	v_pk_mul_f32 v[76:77], v[76:77], v[80:81] op_sel_hi:[1,0]
	v_pk_mul_f32 v[74:75], v[74:75], v[80:81] op_sel_hi:[1,0]
	v_pk_mul_f32 v[72:73], v[72:73], v[80:81] op_sel_hi:[1,0]
	v_pk_mul_f32 v[70:71], v[70:71], v[80:81] op_sel_hi:[1,0]
	v_pk_mul_f32 v[68:69], v[68:69], v[80:81] op_sel_hi:[1,0]
	v_pk_mul_f32 v[84:85], v[66:67], v[80:81] op_sel_hi:[1,0]
	v_pk_mul_f32 v[80:81], v[64:65], v[80:81] op_sel_hi:[1,0]
	v_cvt_pk_bf16_f32 v64, v76, v77
	v_cvt_pk_bf16_f32 v65, v78, v79
	v_cvt_pk_bf16_f32 v66, v72, v73
	v_cvt_pk_bf16_f32 v67, v74, v75
	global_store_dwordx4 v[82:83], v[64:67], off
	s_nop 1
	v_cvt_pk_bf16_f32 v64, v68, v69
	v_cvt_pk_bf16_f32 v65, v70, v71
	v_cvt_pk_bf16_f32 v66, v80, v81
	v_cvt_pk_bf16_f32 v67, v84, v85
	global_store_dwordx4 v[82:83], v[64:67], off offset:256
	s_nop 0
	v_add_co_u32_e32 v68, vcc, s69, v130
	v_lshl_add_u64 v[66:67], v[130:131], 0, s[38:39]
	s_nop 0
	v_addc_co_u32_e32 v69, vcc, 0, v131, vcc
	s_nop 0
	v_mov_b32_e32 v64, v228
	v_pk_mul_f32 v[62:63], v[62:63], v[64:65] op_sel_hi:[1,0]
	v_pk_mul_f32 v[60:61], v[60:61], v[64:65] op_sel_hi:[1,0]
	v_pk_mul_f32 v[58:59], v[58:59], v[64:65] op_sel_hi:[1,0]
	v_pk_mul_f32 v[56:57], v[56:57], v[64:65] op_sel_hi:[1,0]
	v_pk_mul_f32 v[54:55], v[54:55], v[64:65] op_sel_hi:[1,0]
	v_pk_mul_f32 v[52:53], v[52:53], v[64:65] op_sel_hi:[1,0]
	v_pk_mul_f32 v[70:71], v[50:51], v[64:65] op_sel_hi:[1,0]
	v_pk_mul_f32 v[64:65], v[48:49], v[64:65] op_sel_hi:[1,0]
	v_cvt_pk_bf16_f32 v48, v60, v61
	v_cvt_pk_bf16_f32 v49, v62, v63
	v_cvt_pk_bf16_f32 v50, v56, v57
	v_cvt_pk_bf16_f32 v51, v58, v59
	global_store_dwordx4 v[68:69], v[48:51], off
	s_nop 1
	v_cvt_pk_bf16_f32 v48, v52, v53
	v_cvt_pk_bf16_f32 v49, v54, v55
	v_cvt_pk_bf16_f32 v50, v64, v65
	v_cvt_pk_bf16_f32 v51, v70, v71
	global_store_dwordx4 v[66:67], v[48:51], off offset:256
	s_nop 0
	v_add_co_u32_e32 v52, vcc, s70, v130
	v_lshl_add_u64 v[50:51], v[130:131], 0, s[24:25]
	s_nop 0
	v_addc_co_u32_e32 v53, vcc, 0, v131, vcc
	s_nop 0
	v_mov_b32_e32 v48, v229
	v_pk_mul_f32 v[46:47], v[46:47], v[48:49] op_sel_hi:[1,0]
	v_pk_mul_f32 v[44:45], v[44:45], v[48:49] op_sel_hi:[1,0]
	v_pk_mul_f32 v[42:43], v[42:43], v[48:49] op_sel_hi:[1,0]
	v_pk_mul_f32 v[40:41], v[40:41], v[48:49] op_sel_hi:[1,0]
	v_pk_mul_f32 v[38:39], v[38:39], v[48:49] op_sel_hi:[1,0]
	v_pk_mul_f32 v[36:37], v[36:37], v[48:49] op_sel_hi:[1,0]
	v_pk_mul_f32 v[54:55], v[34:35], v[48:49] op_sel_hi:[1,0]
	v_pk_mul_f32 v[48:49], v[32:33], v[48:49] op_sel_hi:[1,0]
	v_cvt_pk_bf16_f32 v32, v44, v45
	v_cvt_pk_bf16_f32 v33, v46, v47
	v_cvt_pk_bf16_f32 v34, v40, v41
	v_cvt_pk_bf16_f32 v35, v42, v43
	global_store_dwordx4 v[52:53], v[32:35], off
	s_nop 1
	v_cvt_pk_bf16_f32 v32, v36, v37
	v_cvt_pk_bf16_f32 v33, v38, v39
	v_cvt_pk_bf16_f32 v34, v48, v49
	v_cvt_pk_bf16_f32 v35, v54, v55
	global_store_dwordx4 v[50:51], v[32:35], off offset:256
	s_nop 0
	v_add_co_u32_e32 v36, vcc, s71, v130
	v_lshl_add_u64 v[34:35], v[130:131], 0, s[44:45]
	s_nop 0
	v_addc_co_u32_e32 v37, vcc, 0, v131, vcc
	s_nop 0
	v_mov_b32_e32 v32, v230
	v_pk_mul_f32 v[30:31], v[30:31], v[32:33] op_sel_hi:[1,0]
	v_pk_mul_f32 v[28:29], v[28:29], v[32:33] op_sel_hi:[1,0]
	v_pk_mul_f32 v[26:27], v[26:27], v[32:33] op_sel_hi:[1,0]
	v_pk_mul_f32 v[24:25], v[24:25], v[32:33] op_sel_hi:[1,0]
	v_pk_mul_f32 v[22:23], v[22:23], v[32:33] op_sel_hi:[1,0]
	v_pk_mul_f32 v[20:21], v[20:21], v[32:33] op_sel_hi:[1,0]
	v_pk_mul_f32 v[38:39], v[18:19], v[32:33] op_sel_hi:[1,0]
	v_pk_mul_f32 v[32:33], v[16:17], v[32:33] op_sel_hi:[1,0]
	v_cvt_pk_bf16_f32 v16, v28, v29
	v_cvt_pk_bf16_f32 v17, v30, v31
	v_cvt_pk_bf16_f32 v18, v24, v25
	v_cvt_pk_bf16_f32 v19, v26, v27
	global_store_dwordx4 v[36:37], v[16:19], off
	s_nop 1
	v_cvt_pk_bf16_f32 v16, v20, v21
	v_cvt_pk_bf16_f32 v17, v22, v23
	v_cvt_pk_bf16_f32 v18, v32, v33
	v_cvt_pk_bf16_f32 v19, v38, v39
	global_store_dwordx4 v[34:35], v[16:19], off offset:256
	s_nop 0
	v_add_co_u32_e32 v20, vcc, s72, v130
	v_lshl_add_u64 v[18:19], v[130:131], 0, s[28:29]
	s_nop 0
	v_addc_co_u32_e32 v21, vcc, 0, v131, vcc
	s_nop 0
	v_mov_b32_e32 v16, v231
	v_pk_mul_f32 v[14:15], v[14:15], v[16:17] op_sel_hi:[1,0]
	v_pk_mul_f32 v[12:13], v[12:13], v[16:17] op_sel_hi:[1,0]
	v_pk_mul_f32 v[10:11], v[10:11], v[16:17] op_sel_hi:[1,0]
	v_pk_mul_f32 v[8:9], v[8:9], v[16:17] op_sel_hi:[1,0]
	v_pk_mul_f32 v[6:7], v[6:7], v[16:17] op_sel_hi:[1,0]
	v_pk_mul_f32 v[4:5], v[4:5], v[16:17] op_sel_hi:[1,0]
	v_pk_mul_f32 v[22:23], v[2:3], v[16:17] op_sel_hi:[1,0]
	v_pk_mul_f32 v[16:17], v[0:1], v[16:17] op_sel_hi:[1,0]
	v_cvt_pk_bf16_f32 v0, v12, v13
	v_cvt_pk_bf16_f32 v1, v14, v15
	v_cvt_pk_bf16_f32 v2, v8, v9
	v_cvt_pk_bf16_f32 v3, v10, v11
	global_store_dwordx4 v[20:21], v[0:3], off
	s_nop 1
	v_cvt_pk_bf16_f32 v0, v4, v5
	v_cvt_pk_bf16_f32 v1, v6, v7
	v_cvt_pk_bf16_f32 v2, v16, v17
	v_cvt_pk_bf16_f32 v3, v22, v23
	global_store_dwordx4 v[18:19], v[0:3], off offset:256
	s_andn2_b64 vcc, exec, s[6:7]
	s_mov_b64 s[6:7], -1
	s_cbranch_vccnz .LBB7_319

.LBB7_980:
	s_or_b64 exec, exec, s[16:17]
	v_mov_b32_e32 v131, 0
	v_mov_b32_e32 v132, 0
	v_mov_b32_e32 v133, 0
	s_and_saveexec_b64 s[16:17], vcc
	s_cbranch_execz .LBB7_1031
	v_ashrrev_i32_e32 v185, 31, v184
	v_lshl_add_u64 v[130:131], v[184:185], 1, v[194:195]
	global_load_dwordx4 v[130:133], v[130:131], off offset:256
	s_or_b64 exec, exec, s[16:17]
	s_waitcnt vmcnt(0)
	v_lshlrev_b64 v[194:195], 11, v[186:187]
	s_and_saveexec_b64 s[16:17], s[42:43]
	s_cbranch_execnz .LBB7_1032

.LBB7_983:
	v_mul_f32_e32 v118, 0xbfb8aa3b, v118
	v_mul_f32_e32 v114, 0xbfb8aa3b, v114
	v_mul_f32_e32 v119, 0xbfb8aa3b, v119
	v_exp_f32_e32 v118, v118
	v_exp_f32_e32 v114, v114
	v_exp_f32_e32 v119, v119
	v_mul_f32_e32 v115, 0xbfb8aa3b, v115
	v_add_f32_e32 v118, 1.0, v118
	v_add_f32_e32 v114, 1.0, v114
	v_add_f32_e32 v119, 1.0, v119
	v_rcp_f32_e32 v118, v118
	v_rcp_f32_e32 v114, v114
	v_rcp_f32_e32 v119, v119
	v_exp_f32_e32 v115, v115
	s_nop 0
	v_lshlrev_b32_e32 v122, 16, v154
	v_and_b32_e32 v123, 0xffff0000, v154
	v_lshlrev_b32_e32 v126, 16, v156
	v_mul_f32_e32 v118, v118, v122
	v_mul_f32_e32 v122, v114, v126
	v_mul_f32_e32 v114, v119, v123
	v_add_f32_e32 v115, 1.0, v115
	v_mul_f32_e32 v119, 0xbfb8aa3b, v120
	v_rcp_f32_e32 v115, v115
	v_exp_f32_e32 v119, v119
	v_and_b32_e32 v127, 0xffff0000, v156
	v_mul_f32_e32 v116, 0xbfb8aa3b, v116
	v_mul_f32_e32 v120, v115, v127
	v_add_f32_e32 v115, 1.0, v119
	v_mul_f32_e32 v119, 0xbfb8aa3b, v121
	v_exp_f32_e32 v116, v116
	v_exp_f32_e32 v119, v119
	v_mul_f32_e32 v117, 0xbfb8aa3b, v117
	v_exp_f32_e32 v117, v117
	v_add_f32_e32 v116, 1.0, v116
	v_add_f32_e32 v119, 1.0, v119
	v_rcp_f32_e32 v116, v116
	v_rcp_f32_e32 v119, v119
	v_add_f32_e32 v117, 1.0, v117
	v_rcp_f32_e32 v115, v115
	v_rcp_f32_e32 v117, v117
	v_and_b32_e32 v125, 0xffff0000, v155
	v_lshlrev_b32_e32 v128, 16, v157
	v_lshlrev_b32_e32 v124, 16, v155
	v_and_b32_e32 v129, 0xffff0000, v157
	v_mul_f32_e32 v121, v116, v128
	v_mul_f32_e32 v116, v119, v125
	v_cvt_pk_bf16_f32 v114, v118, v114
	v_lshl_add_u64 v[118:119], s[64:65], 0, v[194:195]
	v_ashrrev_i32_e32 v185, 31, v184
	v_mul_f32_e32 v115, v115, v124
	v_mul_f32_e32 v117, v117, v129
	v_lshl_add_u64 v[118:119], v[184:185], 1, v[118:119]
	v_cvt_pk_bf16_f32 v115, v115, v116
	v_cvt_pk_bf16_f32 v116, v122, v120
	v_cvt_pk_bf16_f32 v117, v121, v117
	global_store_dwordx4 v[118:119], v[114:117], off offset:256
.LBB7_984:
	s_or_b64 exec, exec, s[16:17]
	v_ashrrev_i32_e32 v193, 31, v192
	v_lshlrev_b64 v[114:115], 11, v[192:193]
	s_and_saveexec_b64 s[16:17], s[42:43]
	s_cbranch_execz .LBB7_986
	v_mul_f32_e32 v110, 0xbfb8aa3b, v110
	v_mul_f32_e32 v106, 0xbfb8aa3b, v106
	v_mul_f32_e32 v111, 0xbfb8aa3b, v111
	v_exp_f32_e32 v110, v110
	v_exp_f32_e32 v106, v106
	v_exp_f32_e32 v111, v111
	v_mul_f32_e32 v107, 0xbfb8aa3b, v107
	v_add_f32_e32 v110, 1.0, v110
	v_add_f32_e32 v106, 1.0, v106
	v_add_f32_e32 v111, 1.0, v111
	v_rcp_f32_e32 v110, v110
	v_rcp_f32_e32 v106, v106
	v_rcp_f32_e32 v111, v111
	v_exp_f32_e32 v107, v107
	s_nop 0
	v_lshlrev_b32_e32 v116, 16, v150
	v_and_b32_e32 v117, 0xffff0000, v150
	v_lshlrev_b32_e32 v120, 16, v152
	v_mul_f32_e32 v110, v110, v116
	v_mul_f32_e32 v116, v106, v120
	v_mul_f32_e32 v106, v111, v117
	v_add_f32_e32 v107, 1.0, v107
	v_mul_f32_e32 v111, 0xbfb8aa3b, v112
	v_rcp_f32_e32 v107, v107
	v_exp_f32_e32 v111, v111
	v_and_b32_e32 v121, 0xffff0000, v152
	v_mul_f32_e32 v108, 0xbfb8aa3b, v108
	v_mul_f32_e32 v112, v107, v121
	v_add_f32_e32 v107, 1.0, v111
	v_mul_f32_e32 v111, 0xbfb8aa3b, v113
	v_exp_f32_e32 v108, v108
	v_exp_f32_e32 v111, v111
	v_mul_f32_e32 v109, 0xbfb8aa3b, v109
	v_exp_f32_e32 v109, v109
	v_add_f32_e32 v108, 1.0, v108
	v_add_f32_e32 v111, 1.0, v111
	v_rcp_f32_e32 v108, v108
	v_rcp_f32_e32 v111, v111
	v_add_f32_e32 v109, 1.0, v109
	v_rcp_f32_e32 v107, v107
	v_rcp_f32_e32 v109, v109
	v_and_b32_e32 v119, 0xffff0000, v151
	v_lshlrev_b32_e32 v122, 16, v153
	v_lshlrev_b32_e32 v118, 16, v151
	v_and_b32_e32 v123, 0xffff0000, v153
	v_mul_f32_e32 v113, v108, v122
	v_mul_f32_e32 v108, v111, v119
	v_cvt_pk_bf16_f32 v106, v110, v106
	v_lshl_add_u64 v[110:111], s[64:65], 0, v[114:115]
	v_ashrrev_i32_e32 v185, 31, v184
	v_mul_f32_e32 v107, v107, v118
	v_mul_f32_e32 v109, v109, v123
	v_lshl_add_u64 v[110:111], v[184:185], 1, v[110:111]
	v_cvt_pk_bf16_f32 v107, v107, v108
	v_cvt_pk_bf16_f32 v108, v116, v112
	v_cvt_pk_bf16_f32 v109, v113, v109
	global_store_dwordx4 v[110:111], v[106:109], off
.LBB7_986:
	s_or_b64 exec, exec, s[16:17]
	s_and_saveexec_b64 s[16:17], vcc
	s_cbranch_execz .LBB7_988
	v_mul_f32_e32 v102, 0xbfb8aa3b, v102
	v_mul_f32_e32 v98, 0xbfb8aa3b, v98
	v_mul_f32_e32 v103, 0xbfb8aa3b, v103
	v_exp_f32_e32 v102, v102
	v_exp_f32_e32 v98, v98
	v_exp_f32_e32 v103, v103
	v_mul_f32_e32 v99, 0xbfb8aa3b, v99
	v_add_f32_e32 v102, 1.0, v102
	v_add_f32_e32 v98, 1.0, v98
	v_add_f32_e32 v103, 1.0, v103
	v_rcp_f32_e32 v102, v102
	v_rcp_f32_e32 v98, v98
	v_rcp_f32_e32 v103, v103
	v_exp_f32_e32 v99, v99
	s_nop 0
	v_lshlrev_b32_e32 v106, 16, v146
	v_and_b32_e32 v107, 0xffff0000, v146
	v_lshlrev_b32_e32 v110, 16, v148
	v_mul_f32_e32 v102, v102, v106
	v_mul_f32_e32 v106, v98, v110
	v_mul_f32_e32 v98, v103, v107
	v_add_f32_e32 v99, 1.0, v99
	v_mul_f32_e32 v103, 0xbfb8aa3b, v104
	v_rcp_f32_e32 v99, v99
	v_exp_f32_e32 v103, v103
	v_and_b32_e32 v111, 0xffff0000, v148
	v_mul_f32_e32 v100, 0xbfb8aa3b, v100
	v_mul_f32_e32 v104, v99, v111
	v_add_f32_e32 v99, 1.0, v103
	v_mul_f32_e32 v103, 0xbfb8aa3b, v105
	v_exp_f32_e32 v100, v100
	v_exp_f32_e32 v103, v103
	v_mul_f32_e32 v101, 0xbfb8aa3b, v101
	v_exp_f32_e32 v101, v101
	v_add_f32_e32 v100, 1.0, v100
	v_add_f32_e32 v103, 1.0, v103
	v_rcp_f32_e32 v100, v100
	v_rcp_f32_e32 v103, v103
	v_add_f32_e32 v101, 1.0, v101
	v_rcp_f32_e32 v99, v99
	v_rcp_f32_e32 v101, v101
	v_and_b32_e32 v109, 0xffff0000, v147
	v_lshlrev_b32_e32 v112, 16, v149
	v_lshlrev_b32_e32 v108, 16, v147
	v_and_b32_e32 v113, 0xffff0000, v149
	v_mul_f32_e32 v105, v100, v112
	v_mul_f32_e32 v100, v103, v109
	v_cvt_pk_bf16_f32 v98, v102, v98
	v_lshl_add_u64 v[102:103], s[64:65], 0, v[114:115]
	v_ashrrev_i32_e32 v185, 31, v184
	v_mul_f32_e32 v99, v99, v108
	v_mul_f32_e32 v101, v101, v113
	v_lshl_add_u64 v[102:103], v[184:185], 1, v[102:103]
	v_cvt_pk_bf16_f32 v99, v99, v100
	v_cvt_pk_bf16_f32 v100, v106, v104
	v_cvt_pk_bf16_f32 v101, v105, v101
	global_store_dwordx4 v[102:103], v[98:101], off offset:256
.LBB7_988:
	s_or_b64 exec, exec, s[16:17]
	v_ashrrev_i32_e32 v191, 31, v190
	v_lshlrev_b64 v[98:99], 11, v[190:191]
	s_and_saveexec_b64 s[16:17], s[42:43]
	s_cbranch_execz .LBB7_990
	v_mul_f32_e32 v94, 0xbfb8aa3b, v94
	v_mul_f32_e32 v90, 0xbfb8aa3b, v90
	v_mul_f32_e32 v95, 0xbfb8aa3b, v95
	v_exp_f32_e32 v94, v94
	v_exp_f32_e32 v90, v90
	v_exp_f32_e32 v95, v95
	v_mul_f32_e32 v91, 0xbfb8aa3b, v91
	v_add_f32_e32 v94, 1.0, v94
	v_add_f32_e32 v90, 1.0, v90
	v_add_f32_e32 v95, 1.0, v95
	v_rcp_f32_e32 v94, v94
	v_rcp_f32_e32 v90, v90
	v_rcp_f32_e32 v95, v95
	v_exp_f32_e32 v91, v91
	s_nop 0
	v_lshlrev_b32_e32 v100, 16, v142
	v_and_b32_e32 v101, 0xffff0000, v142
	v_lshlrev_b32_e32 v104, 16, v144
	v_mul_f32_e32 v94, v94, v100
	v_mul_f32_e32 v100, v90, v104
	v_mul_f32_e32 v90, v95, v101
	v_add_f32_e32 v91, 1.0, v91
	v_mul_f32_e32 v95, 0xbfb8aa3b, v96
	v_rcp_f32_e32 v91, v91
	v_exp_f32_e32 v95, v95
	v_and_b32_e32 v105, 0xffff0000, v144
	v_mul_f32_e32 v92, 0xbfb8aa3b, v92
	v_mul_f32_e32 v96, v91, v105
	v_add_f32_e32 v91, 1.0, v95
	v_mul_f32_e32 v95, 0xbfb8aa3b, v97
	v_exp_f32_e32 v92, v92
	v_exp_f32_e32 v95, v95
	v_mul_f32_e32 v93, 0xbfb8aa3b, v93
	v_exp_f32_e32 v93, v93
	v_add_f32_e32 v92, 1.0, v92
	v_add_f32_e32 v95, 1.0, v95
	v_rcp_f32_e32 v92, v92
	v_rcp_f32_e32 v95, v95
	v_add_f32_e32 v93, 1.0, v93
	v_rcp_f32_e32 v91, v91
	v_rcp_f32_e32 v93, v93
	v_and_b32_e32 v103, 0xffff0000, v143
	v_lshlrev_b32_e32 v106, 16, v145
	v_lshlrev_b32_e32 v102, 16, v143
	v_and_b32_e32 v107, 0xffff0000, v145
	v_mul_f32_e32 v97, v92, v106
	v_mul_f32_e32 v92, v95, v103
	v_cvt_pk_bf16_f32 v90, v94, v90
	v_lshl_add_u64 v[94:95], s[64:65], 0, v[98:99]
	v_ashrrev_i32_e32 v185, 31, v184
	v_mul_f32_e32 v91, v91, v102
	v_mul_f32_e32 v93, v93, v107
	v_lshl_add_u64 v[94:95], v[184:185], 1, v[94:95]
	v_cvt_pk_bf16_f32 v91, v91, v92
	v_cvt_pk_bf16_f32 v92, v100, v96
	v_cvt_pk_bf16_f32 v93, v97, v93
	global_store_dwordx4 v[94:95], v[90:93], off
.LBB7_990:
	s_or_b64 exec, exec, s[16:17]
	s_and_saveexec_b64 s[16:17], vcc
	s_cbranch_execz .LBB7_992
	v_mul_f32_e32 v86, 0xbfb8aa3b, v86
	v_mul_f32_e32 v82, 0xbfb8aa3b, v82
	v_mul_f32_e32 v87, 0xbfb8aa3b, v87
	v_exp_f32_e32 v86, v86
	v_exp_f32_e32 v82, v82
	v_exp_f32_e32 v87, v87
	v_mul_f32_e32 v83, 0xbfb8aa3b, v83
	v_add_f32_e32 v86, 1.0, v86
	v_add_f32_e32 v82, 1.0, v82
	v_add_f32_e32 v87, 1.0, v87
	v_rcp_f32_e32 v86, v86
	v_rcp_f32_e32 v82, v82
	v_rcp_f32_e32 v87, v87
	v_exp_f32_e32 v83, v83
	s_nop 0
	v_lshlrev_b32_e32 v90, 16, v138
	v_and_b32_e32 v91, 0xffff0000, v138
	v_lshlrev_b32_e32 v94, 16, v140
	v_mul_f32_e32 v86, v86, v90
	v_mul_f32_e32 v90, v82, v94
	v_mul_f32_e32 v82, v87, v91
	v_add_f32_e32 v83, 1.0, v83
	v_mul_f32_e32 v87, 0xbfb8aa3b, v88
	v_rcp_f32_e32 v83, v83
	v_exp_f32_e32 v87, v87
	v_and_b32_e32 v95, 0xffff0000, v140
	v_mul_f32_e32 v84, 0xbfb8aa3b, v84
	v_mul_f32_e32 v88, v83, v95
	v_add_f32_e32 v83, 1.0, v87
	v_mul_f32_e32 v87, 0xbfb8aa3b, v89
	v_exp_f32_e32 v84, v84
	v_exp_f32_e32 v87, v87
	v_mul_f32_e32 v85, 0xbfb8aa3b, v85
	v_exp_f32_e32 v85, v85
	v_add_f32_e32 v84, 1.0, v84
	v_add_f32_e32 v87, 1.0, v87
	v_rcp_f32_e32 v84, v84
	v_rcp_f32_e32 v87, v87
	v_add_f32_e32 v85, 1.0, v85
	v_rcp_f32_e32 v83, v83
	v_rcp_f32_e32 v85, v85
	v_and_b32_e32 v93, 0xffff0000, v139
	v_lshlrev_b32_e32 v96, 16, v141
	v_lshlrev_b32_e32 v92, 16, v139
	v_and_b32_e32 v97, 0xffff0000, v141
	v_mul_f32_e32 v89, v84, v96
	v_mul_f32_e32 v84, v87, v93
	v_cvt_pk_bf16_f32 v82, v86, v82
	v_lshl_add_u64 v[86:87], s[64:65], 0, v[98:99]
	v_ashrrev_i32_e32 v185, 31, v184
	v_mul_f32_e32 v83, v83, v92
	v_mul_f32_e32 v85, v85, v97
	v_lshl_add_u64 v[86:87], v[184:185], 1, v[86:87]
	v_cvt_pk_bf16_f32 v83, v83, v84
	v_cvt_pk_bf16_f32 v84, v90, v88
	v_cvt_pk_bf16_f32 v85, v89, v85
	global_store_dwordx4 v[86:87], v[82:85], off offset:256
.LBB7_992:
	s_or_b64 exec, exec, s[16:17]
	v_ashrrev_i32_e32 v189, 31, v188
	v_lshlrev_b64 v[82:83], 11, v[188:189]
	s_and_saveexec_b64 s[16:17], s[42:43]
	s_cbranch_execz .LBB7_994
	v_mul_f32_e32 v78, 0xbfb8aa3b, v78
	v_mul_f32_e32 v74, 0xbfb8aa3b, v74
	v_mul_f32_e32 v79, 0xbfb8aa3b, v79
	v_exp_f32_e32 v78, v78
	v_exp_f32_e32 v74, v74
	v_exp_f32_e32 v79, v79
	v_mul_f32_e32 v75, 0xbfb8aa3b, v75
	v_add_f32_e32 v78, 1.0, v78
	v_add_f32_e32 v74, 1.0, v74
	v_add_f32_e32 v79, 1.0, v79
	v_rcp_f32_e32 v78, v78
	v_rcp_f32_e32 v74, v74
	v_rcp_f32_e32 v79, v79
	v_exp_f32_e32 v75, v75
	s_nop 0
	v_lshlrev_b32_e32 v84, 16, v134
	v_and_b32_e32 v85, 0xffff0000, v134
	v_lshlrev_b32_e32 v88, 16, v136
	v_mul_f32_e32 v78, v78, v84
	v_mul_f32_e32 v84, v74, v88
	v_mul_f32_e32 v74, v79, v85
	v_add_f32_e32 v75, 1.0, v75
	v_mul_f32_e32 v79, 0xbfb8aa3b, v80
	v_rcp_f32_e32 v75, v75
	v_exp_f32_e32 v79, v79
	v_and_b32_e32 v89, 0xffff0000, v136
	v_mul_f32_e32 v76, 0xbfb8aa3b, v76
	v_mul_f32_e32 v80, v75, v89
	v_add_f32_e32 v75, 1.0, v79
	v_mul_f32_e32 v79, 0xbfb8aa3b, v81
	v_exp_f32_e32 v76, v76
	v_exp_f32_e32 v79, v79
	v_mul_f32_e32 v77, 0xbfb8aa3b, v77
	v_exp_f32_e32 v77, v77
	v_add_f32_e32 v76, 1.0, v76
	v_add_f32_e32 v79, 1.0, v79
	v_rcp_f32_e32 v76, v76
	v_rcp_f32_e32 v79, v79
	v_add_f32_e32 v77, 1.0, v77
	v_rcp_f32_e32 v75, v75
	v_rcp_f32_e32 v77, v77
	v_and_b32_e32 v87, 0xffff0000, v135
	v_lshlrev_b32_e32 v90, 16, v137
	v_lshlrev_b32_e32 v86, 16, v135
	v_and_b32_e32 v91, 0xffff0000, v137
	v_mul_f32_e32 v81, v76, v90
	v_mul_f32_e32 v76, v79, v87
	v_cvt_pk_bf16_f32 v74, v78, v74
	v_lshl_add_u64 v[78:79], s[64:65], 0, v[82:83]
	v_ashrrev_i32_e32 v185, 31, v184
	v_mul_f32_e32 v75, v75, v86
	v_mul_f32_e32 v77, v77, v91
	v_lshl_add_u64 v[78:79], v[184:185], 1, v[78:79]
	v_cvt_pk_bf16_f32 v75, v75, v76
	v_cvt_pk_bf16_f32 v76, v84, v80
	v_cvt_pk_bf16_f32 v77, v81, v77
	global_store_dwordx4 v[78:79], v[74:77], off
.LBB7_994:
	s_or_b64 exec, exec, s[16:17]
	s_and_saveexec_b64 s[16:17], vcc
	s_cbranch_execz .LBB7_996
	v_mul_f32_e32 v70, 0xbfb8aa3b, v70
	v_mul_f32_e32 v66, 0xbfb8aa3b, v66
	v_mul_f32_e32 v71, 0xbfb8aa3b, v71
	v_exp_f32_e32 v70, v70
	v_exp_f32_e32 v66, v66
	v_exp_f32_e32 v71, v71
	v_mul_f32_e32 v67, 0xbfb8aa3b, v67
	v_add_f32_e32 v70, 1.0, v70
	v_add_f32_e32 v66, 1.0, v66
	v_add_f32_e32 v71, 1.0, v71
	v_rcp_f32_e32 v70, v70
	v_rcp_f32_e32 v66, v66
	v_rcp_f32_e32 v71, v71
	v_exp_f32_e32 v67, v67
	s_nop 0
	v_lshlrev_b32_e32 v74, 16, v130
	v_and_b32_e32 v75, 0xffff0000, v130
	v_lshlrev_b32_e32 v78, 16, v132
	v_mul_f32_e32 v70, v70, v74
	v_mul_f32_e32 v74, v66, v78
	v_mul_f32_e32 v66, v71, v75
	v_add_f32_e32 v67, 1.0, v67
	v_mul_f32_e32 v71, 0xbfb8aa3b, v72
	v_rcp_f32_e32 v67, v67
	v_exp_f32_e32 v71, v71
	v_and_b32_e32 v79, 0xffff0000, v132
	v_mul_f32_e32 v68, 0xbfb8aa3b, v68
	v_mul_f32_e32 v72, v67, v79
	v_add_f32_e32 v67, 1.0, v71
	v_mul_f32_e32 v71, 0xbfb8aa3b, v73
	v_exp_f32_e32 v68, v68
	v_exp_f32_e32 v71, v71
	v_mul_f32_e32 v69, 0xbfb8aa3b, v69
	v_exp_f32_e32 v69, v69
	v_add_f32_e32 v68, 1.0, v68
	v_add_f32_e32 v71, 1.0, v71
	v_rcp_f32_e32 v68, v68
	v_rcp_f32_e32 v71, v71
	v_add_f32_e32 v69, 1.0, v69
	v_rcp_f32_e32 v67, v67
	v_rcp_f32_e32 v69, v69
	v_and_b32_e32 v77, 0xffff0000, v131
	v_lshlrev_b32_e32 v80, 16, v133
	v_lshlrev_b32_e32 v76, 16, v131
	v_and_b32_e32 v81, 0xffff0000, v133
	v_mul_f32_e32 v73, v68, v80
	v_mul_f32_e32 v68, v71, v77
	v_cvt_pk_bf16_f32 v66, v70, v66
	v_lshl_add_u64 v[70:71], s[64:65], 0, v[82:83]
	v_ashrrev_i32_e32 v185, 31, v184
	v_mul_f32_e32 v67, v67, v76
	v_mul_f32_e32 v69, v69, v81
	v_lshl_add_u64 v[70:71], v[184:185], 1, v[70:71]
	v_cvt_pk_bf16_f32 v67, v67, v68
	v_cvt_pk_bf16_f32 v68, v74, v72
	v_cvt_pk_bf16_f32 v69, v73, v69
	global_store_dwordx4 v[70:71], v[66:69], off offset:256

.LBB7_1012:
	s_or_b64 exec, exec, s[16:17]
	s_waitcnt vmcnt(0)
	v_ashrrev_i32_e32 v105, 31, v104
	v_lshlrev_b64 v[104:105], 11, v[104:105]
	s_and_saveexec_b64 s[16:17], s[42:43]
	s_cbranch_execz .LBB7_1014
	v_mul_f32_e32 v62, 0xbfb8aa3b, v62
	v_mul_f32_e32 v58, 0xbfb8aa3b, v58
	v_mul_f32_e32 v63, 0xbfb8aa3b, v63
	v_exp_f32_e32 v62, v62
	v_exp_f32_e32 v58, v58
	v_exp_f32_e32 v63, v63
	v_mul_f32_e32 v59, 0xbfb8aa3b, v59
	v_add_f32_e32 v62, 1.0, v62
	v_add_f32_e32 v58, 1.0, v58
	v_add_f32_e32 v63, 1.0, v63
	v_rcp_f32_e32 v62, v62
	v_rcp_f32_e32 v58, v58
	v_rcp_f32_e32 v63, v63
	v_exp_f32_e32 v59, v59
	s_nop 0
	v_lshlrev_b32_e32 v99, 16, v94
	v_and_b32_e32 v94, 0xffff0000, v94
	v_lshlrev_b32_e32 v103, 16, v96
	v_mul_f32_e32 v62, v62, v99
	v_mul_f32_e32 v99, v58, v103
	v_mul_f32_e32 v58, v63, v94
	v_add_f32_e32 v59, 1.0, v59
	v_mul_f32_e32 v63, 0xbfb8aa3b, v64
	v_rcp_f32_e32 v59, v59
	v_exp_f32_e32 v63, v63
	v_and_b32_e32 v96, 0xffff0000, v96
	v_mul_f32_e32 v60, 0xbfb8aa3b, v60
	v_mul_f32_e32 v64, v59, v96
	v_add_f32_e32 v59, 1.0, v63
	v_mul_f32_e32 v63, 0xbfb8aa3b, v65
	v_exp_f32_e32 v60, v60
	v_exp_f32_e32 v63, v63
	v_mul_f32_e32 v61, 0xbfb8aa3b, v61
	v_exp_f32_e32 v61, v61
	v_add_f32_e32 v60, 1.0, v60
	v_add_f32_e32 v63, 1.0, v63
	v_rcp_f32_e32 v60, v60
	v_rcp_f32_e32 v63, v63
	v_add_f32_e32 v61, 1.0, v61
	v_rcp_f32_e32 v59, v59
	v_rcp_f32_e32 v61, v61
	v_lshlrev_b32_e32 v101, 16, v95
	v_and_b32_e32 v95, 0xffff0000, v95
	v_lshlrev_b32_e32 v106, 16, v97
	v_and_b32_e32 v97, 0xffff0000, v97
	v_mul_f32_e32 v65, v60, v106
	v_mul_f32_e32 v60, v63, v95
	v_cvt_pk_bf16_f32 v58, v62, v58
	v_lshl_add_u64 v[62:63], s[64:65], 0, v[104:105]
	v_ashrrev_i32_e32 v185, 31, v184
	v_mul_f32_e32 v59, v59, v101
	v_mul_f32_e32 v61, v61, v97
	v_lshl_add_u64 v[62:63], v[184:185], 1, v[62:63]
	v_cvt_pk_bf16_f32 v59, v59, v60
	v_cvt_pk_bf16_f32 v60, v99, v64
	v_cvt_pk_bf16_f32 v61, v65, v61
	global_store_dwordx4 v[62:63], v[58:61], off
.LBB7_1014:
	s_or_b64 exec, exec, s[16:17]
	s_and_saveexec_b64 s[16:17], vcc
	s_cbranch_execz .LBB7_1016
	v_mul_f32_e32 v54, 0xbfb8aa3b, v54
	v_mul_f32_e32 v50, 0xbfb8aa3b, v50
	v_mul_f32_e32 v55, 0xbfb8aa3b, v55
	v_exp_f32_e32 v54, v54
	v_exp_f32_e32 v50, v50
	v_exp_f32_e32 v55, v55
	v_mul_f32_e32 v51, 0xbfb8aa3b, v51
	v_add_f32_e32 v54, 1.0, v54
	v_add_f32_e32 v50, 1.0, v50
	v_add_f32_e32 v55, 1.0, v55
	v_rcp_f32_e32 v54, v54
	v_rcp_f32_e32 v50, v50
	v_rcp_f32_e32 v55, v55
	v_exp_f32_e32 v51, v51
	s_nop 0
	v_lshlrev_b32_e32 v58, 16, v90
	v_and_b32_e32 v59, 0xffff0000, v90
	v_lshlrev_b32_e32 v62, 16, v92
	v_mul_f32_e32 v54, v54, v58
	v_mul_f32_e32 v58, v50, v62
	v_mul_f32_e32 v50, v55, v59
	v_add_f32_e32 v51, 1.0, v51
	v_mul_f32_e32 v55, 0xbfb8aa3b, v56
	v_rcp_f32_e32 v51, v51
	v_exp_f32_e32 v55, v55
	v_and_b32_e32 v63, 0xffff0000, v92
	v_mul_f32_e32 v52, 0xbfb8aa3b, v52
	v_mul_f32_e32 v56, v51, v63
	v_add_f32_e32 v51, 1.0, v55
	v_mul_f32_e32 v55, 0xbfb8aa3b, v57
	v_exp_f32_e32 v52, v52
	v_exp_f32_e32 v55, v55
	v_mul_f32_e32 v53, 0xbfb8aa3b, v53
	v_exp_f32_e32 v53, v53
	v_add_f32_e32 v52, 1.0, v52
	v_add_f32_e32 v55, 1.0, v55
	v_rcp_f32_e32 v52, v52
	v_rcp_f32_e32 v55, v55
	v_add_f32_e32 v53, 1.0, v53
	v_rcp_f32_e32 v51, v51
	v_rcp_f32_e32 v53, v53
	v_and_b32_e32 v61, 0xffff0000, v91
	v_lshlrev_b32_e32 v64, 16, v93
	v_lshlrev_b32_e32 v60, 16, v91
	v_and_b32_e32 v65, 0xffff0000, v93
	v_mul_f32_e32 v57, v52, v64
	v_mul_f32_e32 v52, v55, v61
	v_cvt_pk_bf16_f32 v50, v54, v50
	v_lshl_add_u64 v[54:55], s[64:65], 0, v[104:105]
	v_ashrrev_i32_e32 v185, 31, v184
	v_mul_f32_e32 v51, v51, v60
	v_mul_f32_e32 v53, v53, v65
	v_lshl_add_u64 v[54:55], v[184:185], 1, v[54:55]
	v_cvt_pk_bf16_f32 v51, v51, v52
	v_cvt_pk_bf16_f32 v52, v58, v56
	v_cvt_pk_bf16_f32 v53, v57, v53
	global_store_dwordx4 v[54:55], v[50:53], off offset:256
.LBB7_1016:
	s_or_b64 exec, exec, s[16:17]
	v_ashrrev_i32_e32 v103, 31, v102
	v_lshlrev_b64 v[50:51], 11, v[102:103]
	s_and_saveexec_b64 s[16:17], s[42:43]
	s_cbranch_execz .LBB7_1018
	v_mul_f32_e32 v46, 0xbfb8aa3b, v46
	v_mul_f32_e32 v42, 0xbfb8aa3b, v42
	v_mul_f32_e32 v47, 0xbfb8aa3b, v47
	v_exp_f32_e32 v46, v46
	v_exp_f32_e32 v42, v42
	v_exp_f32_e32 v47, v47
	v_mul_f32_e32 v43, 0xbfb8aa3b, v43
	v_add_f32_e32 v46, 1.0, v46
	v_add_f32_e32 v42, 1.0, v42
	v_add_f32_e32 v47, 1.0, v47
	v_rcp_f32_e32 v46, v46
	v_rcp_f32_e32 v42, v42
	v_rcp_f32_e32 v47, v47
	v_exp_f32_e32 v43, v43
	s_nop 0
	v_lshlrev_b32_e32 v52, 16, v86
	v_and_b32_e32 v53, 0xffff0000, v86
	v_lshlrev_b32_e32 v56, 16, v88
	v_mul_f32_e32 v46, v46, v52
	v_mul_f32_e32 v52, v42, v56
	v_mul_f32_e32 v42, v47, v53
	v_add_f32_e32 v43, 1.0, v43
	v_mul_f32_e32 v47, 0xbfb8aa3b, v48
	v_rcp_f32_e32 v43, v43
	v_exp_f32_e32 v47, v47
	v_and_b32_e32 v57, 0xffff0000, v88
	v_mul_f32_e32 v44, 0xbfb8aa3b, v44
	v_mul_f32_e32 v48, v43, v57
	v_add_f32_e32 v43, 1.0, v47
	v_mul_f32_e32 v47, 0xbfb8aa3b, v49
	v_exp_f32_e32 v44, v44
	v_exp_f32_e32 v47, v47
	v_mul_f32_e32 v45, 0xbfb8aa3b, v45
	v_exp_f32_e32 v45, v45
	v_add_f32_e32 v44, 1.0, v44
	v_add_f32_e32 v47, 1.0, v47
	v_rcp_f32_e32 v44, v44
	v_rcp_f32_e32 v47, v47
	v_add_f32_e32 v45, 1.0, v45
	v_rcp_f32_e32 v43, v43
	v_rcp_f32_e32 v45, v45
	v_and_b32_e32 v55, 0xffff0000, v87
	v_lshlrev_b32_e32 v58, 16, v89
	v_lshlrev_b32_e32 v54, 16, v87
	v_and_b32_e32 v59, 0xffff0000, v89
	v_mul_f32_e32 v49, v44, v58
	v_mul_f32_e32 v44, v47, v55
	v_cvt_pk_bf16_f32 v42, v46, v42
	v_lshl_add_u64 v[46:47], s[64:65], 0, v[50:51]
	v_ashrrev_i32_e32 v185, 31, v184
	v_mul_f32_e32 v43, v43, v54
	v_mul_f32_e32 v45, v45, v59
	v_lshl_add_u64 v[46:47], v[184:185], 1, v[46:47]
	v_cvt_pk_bf16_f32 v43, v43, v44
	v_cvt_pk_bf16_f32 v44, v52, v48
	v_cvt_pk_bf16_f32 v45, v49, v45
	global_store_dwordx4 v[46:47], v[42:45], off
.LBB7_1018:
	s_or_b64 exec, exec, s[16:17]
	s_and_saveexec_b64 s[16:17], vcc
	s_cbranch_execz .LBB7_1020
	v_mul_f32_e32 v38, 0xbfb8aa3b, v38
	v_mul_f32_e32 v34, 0xbfb8aa3b, v34
	v_mul_f32_e32 v39, 0xbfb8aa3b, v39
	v_exp_f32_e32 v38, v38
	v_exp_f32_e32 v34, v34
	v_exp_f32_e32 v39, v39
	v_mul_f32_e32 v35, 0xbfb8aa3b, v35
	v_add_f32_e32 v38, 1.0, v38
	v_add_f32_e32 v34, 1.0, v34
	v_add_f32_e32 v39, 1.0, v39
	v_rcp_f32_e32 v38, v38
	v_rcp_f32_e32 v34, v34
	v_rcp_f32_e32 v39, v39
	v_exp_f32_e32 v35, v35
	s_nop 0
	v_lshlrev_b32_e32 v42, 16, v82
	v_and_b32_e32 v43, 0xffff0000, v82
	v_lshlrev_b32_e32 v46, 16, v84
	v_mul_f32_e32 v38, v38, v42
	v_mul_f32_e32 v42, v34, v46
	v_mul_f32_e32 v34, v39, v43
	v_add_f32_e32 v35, 1.0, v35
	v_mul_f32_e32 v39, 0xbfb8aa3b, v40
	v_rcp_f32_e32 v35, v35
	v_exp_f32_e32 v39, v39
	v_and_b32_e32 v47, 0xffff0000, v84
	v_mul_f32_e32 v36, 0xbfb8aa3b, v36
	v_mul_f32_e32 v40, v35, v47
	v_add_f32_e32 v35, 1.0, v39
	v_mul_f32_e32 v39, 0xbfb8aa3b, v41
	v_exp_f32_e32 v36, v36
	v_exp_f32_e32 v39, v39
	v_mul_f32_e32 v37, 0xbfb8aa3b, v37
	v_exp_f32_e32 v37, v37
	v_add_f32_e32 v36, 1.0, v36
	v_add_f32_e32 v39, 1.0, v39
	v_rcp_f32_e32 v36, v36
	v_rcp_f32_e32 v39, v39
	v_add_f32_e32 v37, 1.0, v37
	v_rcp_f32_e32 v35, v35
	v_rcp_f32_e32 v37, v37
	v_and_b32_e32 v45, 0xffff0000, v83
	v_lshlrev_b32_e32 v48, 16, v85
	v_lshlrev_b32_e32 v44, 16, v83
	v_and_b32_e32 v49, 0xffff0000, v85
	v_mul_f32_e32 v41, v36, v48
	v_mul_f32_e32 v36, v39, v45
	v_cvt_pk_bf16_f32 v34, v38, v34
	v_lshl_add_u64 v[38:39], s[64:65], 0, v[50:51]
	v_ashrrev_i32_e32 v185, 31, v184
	v_mul_f32_e32 v35, v35, v44
	v_mul_f32_e32 v37, v37, v49
	v_lshl_add_u64 v[38:39], v[184:185], 1, v[38:39]
	v_cvt_pk_bf16_f32 v35, v35, v36
	v_cvt_pk_bf16_f32 v36, v42, v40
	v_cvt_pk_bf16_f32 v37, v41, v37
	global_store_dwordx4 v[38:39], v[34:37], off offset:256
.LBB7_1020:
	s_or_b64 exec, exec, s[16:17]
	v_ashrrev_i32_e32 v101, 31, v100
	v_lshlrev_b64 v[34:35], 11, v[100:101]
	s_and_saveexec_b64 s[16:17], s[42:43]
	s_cbranch_execz .LBB7_1022
	v_mul_f32_e32 v30, 0xbfb8aa3b, v30
	v_mul_f32_e32 v26, 0xbfb8aa3b, v26
	v_mul_f32_e32 v31, 0xbfb8aa3b, v31
	v_exp_f32_e32 v30, v30
	v_exp_f32_e32 v26, v26
	v_exp_f32_e32 v31, v31
	v_mul_f32_e32 v27, 0xbfb8aa3b, v27
	v_add_f32_e32 v30, 1.0, v30
	v_add_f32_e32 v26, 1.0, v26
	v_add_f32_e32 v31, 1.0, v31
	v_rcp_f32_e32 v30, v30
	v_rcp_f32_e32 v26, v26
	v_rcp_f32_e32 v31, v31
	v_exp_f32_e32 v27, v27
	s_nop 0
	v_lshlrev_b32_e32 v36, 16, v78
	v_and_b32_e32 v37, 0xffff0000, v78
	v_lshlrev_b32_e32 v40, 16, v80
	v_mul_f32_e32 v30, v30, v36
	v_mul_f32_e32 v36, v26, v40
	v_mul_f32_e32 v26, v31, v37
	v_add_f32_e32 v27, 1.0, v27
	v_mul_f32_e32 v31, 0xbfb8aa3b, v32
	v_rcp_f32_e32 v27, v27
	v_exp_f32_e32 v31, v31
	v_and_b32_e32 v41, 0xffff0000, v80
	v_mul_f32_e32 v28, 0xbfb8aa3b, v28
	v_mul_f32_e32 v32, v27, v41
	v_add_f32_e32 v27, 1.0, v31
	v_mul_f32_e32 v31, 0xbfb8aa3b, v33
	v_exp_f32_e32 v28, v28
	v_exp_f32_e32 v31, v31
	v_mul_f32_e32 v29, 0xbfb8aa3b, v29
	v_exp_f32_e32 v29, v29
	v_add_f32_e32 v28, 1.0, v28
	v_add_f32_e32 v31, 1.0, v31
	v_rcp_f32_e32 v28, v28
	v_rcp_f32_e32 v31, v31
	v_add_f32_e32 v29, 1.0, v29
	v_rcp_f32_e32 v27, v27
	v_rcp_f32_e32 v29, v29
	v_and_b32_e32 v39, 0xffff0000, v79
	v_lshlrev_b32_e32 v42, 16, v81
	v_lshlrev_b32_e32 v38, 16, v79
	v_and_b32_e32 v43, 0xffff0000, v81
	v_mul_f32_e32 v33, v28, v42
	v_mul_f32_e32 v28, v31, v39
	v_cvt_pk_bf16_f32 v26, v30, v26
	v_lshl_add_u64 v[30:31], s[64:65], 0, v[34:35]
	v_ashrrev_i32_e32 v185, 31, v184
	v_mul_f32_e32 v27, v27, v38
	v_mul_f32_e32 v29, v29, v43
	v_lshl_add_u64 v[30:31], v[184:185], 1, v[30:31]
	v_cvt_pk_bf16_f32 v27, v27, v28
	v_cvt_pk_bf16_f32 v28, v36, v32
	v_cvt_pk_bf16_f32 v29, v33, v29
	global_store_dwordx4 v[30:31], v[26:29], off
.LBB7_1022:
	s_or_b64 exec, exec, s[16:17]
	s_and_saveexec_b64 s[16:17], vcc
	s_cbranch_execz .LBB7_1024
	v_mul_f32_e32 v22, 0xbfb8aa3b, v22
	v_mul_f32_e32 v18, 0xbfb8aa3b, v18
	v_mul_f32_e32 v23, 0xbfb8aa3b, v23
	v_exp_f32_e32 v22, v22
	v_exp_f32_e32 v18, v18
	v_exp_f32_e32 v23, v23
	v_mul_f32_e32 v19, 0xbfb8aa3b, v19
	v_add_f32_e32 v22, 1.0, v22
	v_add_f32_e32 v18, 1.0, v18
	v_add_f32_e32 v23, 1.0, v23
	v_rcp_f32_e32 v22, v22
	v_rcp_f32_e32 v18, v18
	v_rcp_f32_e32 v23, v23
	v_exp_f32_e32 v19, v19
	s_nop 0
	v_lshlrev_b32_e32 v26, 16, v74
	v_and_b32_e32 v27, 0xffff0000, v74
	v_lshlrev_b32_e32 v30, 16, v76
	v_mul_f32_e32 v22, v22, v26
	v_mul_f32_e32 v26, v18, v30
	v_mul_f32_e32 v18, v23, v27
	v_add_f32_e32 v19, 1.0, v19
	v_mul_f32_e32 v23, 0xbfb8aa3b, v24
	v_rcp_f32_e32 v19, v19
	v_exp_f32_e32 v23, v23
	v_and_b32_e32 v31, 0xffff0000, v76
	v_mul_f32_e32 v20, 0xbfb8aa3b, v20
	v_mul_f32_e32 v24, v19, v31
	v_add_f32_e32 v19, 1.0, v23
	v_mul_f32_e32 v23, 0xbfb8aa3b, v25
	v_exp_f32_e32 v20, v20
	v_exp_f32_e32 v23, v23
	v_mul_f32_e32 v21, 0xbfb8aa3b, v21
	v_exp_f32_e32 v21, v21
	v_add_f32_e32 v20, 1.0, v20
	v_add_f32_e32 v23, 1.0, v23
	v_rcp_f32_e32 v20, v20
	v_rcp_f32_e32 v23, v23
	v_add_f32_e32 v21, 1.0, v21
	v_rcp_f32_e32 v19, v19
	v_rcp_f32_e32 v21, v21
	v_and_b32_e32 v29, 0xffff0000, v75
	v_lshlrev_b32_e32 v32, 16, v77
	v_lshlrev_b32_e32 v28, 16, v75
	v_and_b32_e32 v33, 0xffff0000, v77
	v_mul_f32_e32 v25, v20, v32
	v_mul_f32_e32 v20, v23, v29
	v_cvt_pk_bf16_f32 v18, v22, v18
	v_lshl_add_u64 v[22:23], s[64:65], 0, v[34:35]
	v_ashrrev_i32_e32 v185, 31, v184
	v_mul_f32_e32 v19, v19, v28
	v_mul_f32_e32 v21, v21, v33
	v_lshl_add_u64 v[22:23], v[184:185], 1, v[22:23]
	v_cvt_pk_bf16_f32 v19, v19, v20
	v_cvt_pk_bf16_f32 v20, v26, v24
	v_cvt_pk_bf16_f32 v21, v25, v21
	global_store_dwordx4 v[22:23], v[18:21], off offset:256
.LBB7_1024:
	s_or_b64 exec, exec, s[16:17]
	v_ashrrev_i32_e32 v99, 31, v98
	v_lshlrev_b64 v[18:19], 11, v[98:99]
	s_and_saveexec_b64 s[16:17], s[42:43]
	s_cbranch_execz .LBB7_1026
	v_mul_f32_e32 v14, 0xbfb8aa3b, v14
	v_mul_f32_e32 v10, 0xbfb8aa3b, v10
	v_mul_f32_e32 v15, 0xbfb8aa3b, v15
	v_exp_f32_e32 v14, v14
	v_exp_f32_e32 v10, v10
	v_exp_f32_e32 v15, v15
	v_mul_f32_e32 v11, 0xbfb8aa3b, v11
	v_add_f32_e32 v14, 1.0, v14
	v_add_f32_e32 v10, 1.0, v10
	v_add_f32_e32 v15, 1.0, v15
	v_rcp_f32_e32 v14, v14
	v_rcp_f32_e32 v10, v10
	v_rcp_f32_e32 v15, v15
	v_exp_f32_e32 v11, v11
	s_nop 0
	v_lshlrev_b32_e32 v20, 16, v70
	v_and_b32_e32 v21, 0xffff0000, v70
	v_lshlrev_b32_e32 v24, 16, v72
	v_mul_f32_e32 v14, v14, v20
	v_mul_f32_e32 v20, v10, v24
	v_mul_f32_e32 v10, v15, v21
	v_add_f32_e32 v11, 1.0, v11
	v_mul_f32_e32 v15, 0xbfb8aa3b, v16
	v_rcp_f32_e32 v11, v11
	v_exp_f32_e32 v15, v15
	v_and_b32_e32 v25, 0xffff0000, v72
	v_mul_f32_e32 v12, 0xbfb8aa3b, v12
	v_mul_f32_e32 v16, v11, v25
	v_add_f32_e32 v11, 1.0, v15
	v_mul_f32_e32 v15, 0xbfb8aa3b, v17
	v_exp_f32_e32 v12, v12
	v_exp_f32_e32 v15, v15
	v_mul_f32_e32 v13, 0xbfb8aa3b, v13
	v_exp_f32_e32 v13, v13
	v_add_f32_e32 v12, 1.0, v12
	v_add_f32_e32 v15, 1.0, v15
	v_rcp_f32_e32 v12, v12
	v_rcp_f32_e32 v15, v15
	v_add_f32_e32 v13, 1.0, v13
	v_rcp_f32_e32 v11, v11
	v_rcp_f32_e32 v13, v13
	v_and_b32_e32 v23, 0xffff0000, v71
	v_lshlrev_b32_e32 v26, 16, v73
	v_lshlrev_b32_e32 v22, 16, v71
	v_and_b32_e32 v27, 0xffff0000, v73
	v_mul_f32_e32 v17, v12, v26
	v_mul_f32_e32 v12, v15, v23
	v_cvt_pk_bf16_f32 v10, v14, v10
	v_lshl_add_u64 v[14:15], s[64:65], 0, v[18:19]
	v_ashrrev_i32_e32 v185, 31, v184
	v_mul_f32_e32 v11, v11, v22
	v_mul_f32_e32 v13, v13, v27
	v_lshl_add_u64 v[14:15], v[184:185], 1, v[14:15]
	v_cvt_pk_bf16_f32 v11, v11, v12
	v_cvt_pk_bf16_f32 v12, v20, v16
	v_cvt_pk_bf16_f32 v13, v17, v13
	global_store_dwordx4 v[14:15], v[10:13], off
.LBB7_1026:
	s_or_b64 exec, exec, s[16:17]
	s_and_saveexec_b64 s[16:17], vcc
	s_cbranch_execz .LBB7_1028
	v_mul_f32_e32 v6, 0xbfb8aa3b, v6
	v_mul_f32_e32 v2, 0xbfb8aa3b, v2
	v_mul_f32_e32 v7, 0xbfb8aa3b, v7
	v_exp_f32_e32 v6, v6
	v_exp_f32_e32 v2, v2
	v_exp_f32_e32 v7, v7
	v_mul_f32_e32 v3, 0xbfb8aa3b, v3
	v_add_f32_e32 v6, 1.0, v6
	v_add_f32_e32 v2, 1.0, v2
	v_add_f32_e32 v7, 1.0, v7
	v_rcp_f32_e32 v6, v6
	v_rcp_f32_e32 v2, v2
	v_rcp_f32_e32 v7, v7
	v_exp_f32_e32 v3, v3
	s_nop 0
	v_lshlrev_b32_e32 v10, 16, v66
	v_and_b32_e32 v11, 0xffff0000, v66
	v_lshlrev_b32_e32 v14, 16, v68
	v_mul_f32_e32 v6, v6, v10
	v_mul_f32_e32 v10, v2, v14
	v_mul_f32_e32 v2, v7, v11
	v_add_f32_e32 v3, 1.0, v3
	v_mul_f32_e32 v7, 0xbfb8aa3b, v8
	v_rcp_f32_e32 v3, v3
	v_exp_f32_e32 v7, v7
	v_and_b32_e32 v15, 0xffff0000, v68
	v_mul_f32_e32 v4, 0xbfb8aa3b, v4
	v_mul_f32_e32 v8, v3, v15
	v_add_f32_e32 v3, 1.0, v7
	v_mul_f32_e32 v7, 0xbfb8aa3b, v9
	v_exp_f32_e32 v4, v4
	v_exp_f32_e32 v7, v7
	v_mul_f32_e32 v5, 0xbfb8aa3b, v5
	v_exp_f32_e32 v5, v5
	v_add_f32_e32 v4, 1.0, v4
	v_add_f32_e32 v7, 1.0, v7
	v_rcp_f32_e32 v4, v4
	v_rcp_f32_e32 v7, v7
	v_add_f32_e32 v5, 1.0, v5
	v_rcp_f32_e32 v3, v3
	v_rcp_f32_e32 v5, v5
	v_and_b32_e32 v13, 0xffff0000, v67
	v_lshlrev_b32_e32 v16, 16, v69
	v_lshlrev_b32_e32 v12, 16, v67
	v_and_b32_e32 v17, 0xffff0000, v69
	v_mul_f32_e32 v9, v4, v16
	v_mul_f32_e32 v4, v7, v13
	v_cvt_pk_bf16_f32 v2, v6, v2
	v_lshl_add_u64 v[6:7], s[64:65], 0, v[18:19]
	v_ashrrev_i32_e32 v185, 31, v184
	v_mul_f32_e32 v3, v3, v12
	v_mul_f32_e32 v5, v5, v17
	v_lshl_add_u64 v[6:7], v[184:185], 1, v[6:7]
	v_cvt_pk_bf16_f32 v3, v3, v4
	v_cvt_pk_bf16_f32 v4, v10, v8
	v_cvt_pk_bf16_f32 v5, v9, v5
	global_store_dwordx4 v[6:7], v[2:5], off offset:256

.LBB7_1031:
	s_or_b64 exec, exec, s[16:17]
	s_waitcnt vmcnt(0)
	v_lshlrev_b64 v[194:195], 11, v[186:187]
	s_and_saveexec_b64 s[16:17], s[42:43]
	s_cbranch_execz .LBB7_982
.LBB7_1032:
	v_mul_f32_e32 v126, 0xbfb8aa3b, v126
	v_mul_f32_e32 v122, 0xbfb8aa3b, v122
	v_mul_f32_e32 v127, 0xbfb8aa3b, v127
	v_exp_f32_e32 v126, v126
	v_exp_f32_e32 v122, v122
	v_exp_f32_e32 v127, v127
	v_mul_f32_e32 v123, 0xbfb8aa3b, v123
	v_add_f32_e32 v126, 1.0, v126
	v_add_f32_e32 v122, 1.0, v122
	v_add_f32_e32 v127, 1.0, v127
	v_rcp_f32_e32 v126, v126
	v_rcp_f32_e32 v122, v122
	v_rcp_f32_e32 v127, v127
	v_exp_f32_e32 v123, v123
	s_nop 0
	v_lshlrev_b32_e32 v170, 16, v158
	v_and_b32_e32 v158, 0xffff0000, v158
	v_lshlrev_b32_e32 v172, 16, v160
	v_mul_f32_e32 v126, v126, v170
	v_mul_f32_e32 v170, v122, v172
	v_mul_f32_e32 v122, v127, v158
	v_add_f32_e32 v123, 1.0, v123
	v_mul_f32_e32 v127, 0xbfb8aa3b, v128
	v_rcp_f32_e32 v123, v123
	v_exp_f32_e32 v127, v127
	v_and_b32_e32 v160, 0xffff0000, v160
	v_mul_f32_e32 v124, 0xbfb8aa3b, v124
	v_mul_f32_e32 v128, v123, v160
	v_add_f32_e32 v123, 1.0, v127
	v_mul_f32_e32 v127, 0xbfb8aa3b, v129
	v_exp_f32_e32 v124, v124
	v_exp_f32_e32 v127, v127
	v_mul_f32_e32 v125, 0xbfb8aa3b, v125
	v_exp_f32_e32 v125, v125
	v_add_f32_e32 v124, 1.0, v124
	v_add_f32_e32 v127, 1.0, v127
	v_rcp_f32_e32 v124, v124
	v_rcp_f32_e32 v127, v127
	v_add_f32_e32 v125, 1.0, v125
	v_rcp_f32_e32 v123, v123
	v_rcp_f32_e32 v125, v125
	v_lshlrev_b32_e32 v171, 16, v159
	v_and_b32_e32 v159, 0xffff0000, v159
	v_lshlrev_b32_e32 v173, 16, v161
	v_and_b32_e32 v161, 0xffff0000, v161
	v_mul_f32_e32 v129, v124, v173
	v_mul_f32_e32 v124, v127, v159
	v_cvt_pk_bf16_f32 v122, v126, v122
	v_lshl_add_u64 v[126:127], s[64:65], 0, v[194:195]
	v_ashrrev_i32_e32 v185, 31, v184
	v_mul_f32_e32 v123, v123, v171
	v_mul_f32_e32 v125, v125, v161
	v_lshl_add_u64 v[126:127], v[184:185], 1, v[126:127]
	v_cvt_pk_bf16_f32 v123, v123, v124
	v_cvt_pk_bf16_f32 v124, v170, v128
	v_cvt_pk_bf16_f32 v125, v129, v125
	global_store_dwordx4 v[126:127], v[122:125], off
	s_or_b64 exec, exec, s[16:17]
	s_and_saveexec_b64 s[16:17], vcc
	s_cbranch_execnz .LBB7_983
	s_branch .LBB7_984
